# v75 (64-bit accumulator zeroing) + late extra barrier for the trailing half at GEMM unit seams
# baseline (speedup 1.0000x reference)
.LBB0_125:
	s_ashr_i32 s19, s18, 31
	s_lshl_b64 s[20:21], s[18:19], 19
	s_add_u32 s20, s0, s20
	s_addc_u32 s21, s1, s21
	s_and_b64 s[22:23], s[4:5], exec
	s_cselect_b32 s19, s21, s27
	s_cselect_b32 s45, s20, s26
	s_ashr_i32 s17, s16, 31
	s_lshl_b64 s[22:23], s[16:17], 19
	s_add_u32 s22, s6, s22
	s_addc_u32 s23, s7, s23
	s_and_b64 s[28:29], s[4:5], exec
	s_cselect_b32 s17, s23, s25
	s_cselect_b32 s46, s22, s24
	s_add_u32 s47, s24, 0x100
	s_addc_u32 s48, s25, 0
	s_add_u32 s24, s26, 0x40080
	s_addc_u32 s25, s27, 0
	s_mov_b32 s49, -2
	v_mov_b64_e32 v[0:1], 0
	v_mov_b64_e32 v[2:3], 0
	v_mov_b64_e32 v[4:5], 0
	v_mov_b64_e32 v[6:7], 0
	v_mov_b64_e32 v[8:9], 0
	v_mov_b64_e32 v[10:11], 0
	v_mov_b64_e32 v[12:13], 0
	v_mov_b64_e32 v[14:15], 0
	v_mov_b64_e32 v[16:17], 0
	v_mov_b64_e32 v[18:19], 0
	v_mov_b64_e32 v[20:21], 0
	v_mov_b64_e32 v[22:23], 0
	v_mov_b64_e32 v[24:25], 0
	v_mov_b64_e32 v[26:27], 0
	v_mov_b64_e32 v[28:29], 0
	v_mov_b64_e32 v[30:31], 0
	v_mov_b64_e32 v[32:33], 0
	v_mov_b64_e32 v[34:35], 0
	v_mov_b64_e32 v[36:37], 0
	v_mov_b64_e32 v[38:39], 0
	v_mov_b64_e32 v[40:41], 0
	v_mov_b64_e32 v[42:43], 0
	v_mov_b64_e32 v[44:45], 0
	v_mov_b64_e32 v[46:47], 0
	v_mov_b64_e32 v[48:49], 0
	v_mov_b64_e32 v[50:51], 0
	v_mov_b64_e32 v[52:53], 0
	v_mov_b64_e32 v[54:55], 0
	v_mov_b64_e32 v[56:57], 0
	v_mov_b64_e32 v[58:59], 0
	v_mov_b64_e32 v[60:61], 0
	v_mov_b64_e32 v[62:63], 0
	v_mov_b64_e32 v[64:65], 0
	v_mov_b64_e32 v[66:67], 0
	v_mov_b64_e32 v[68:69], 0
	v_mov_b64_e32 v[70:71], 0
	v_mov_b64_e32 v[72:73], 0
	v_mov_b64_e32 v[74:75], 0
	v_mov_b64_e32 v[76:77], 0
	v_mov_b64_e32 v[78:79], 0
	v_mov_b64_e32 v[80:81], 0
	v_mov_b64_e32 v[82:83], 0
	v_mov_b64_e32 v[84:85], 0
	v_mov_b64_e32 v[86:87], 0
	v_mov_b64_e32 v[88:89], 0
	v_mov_b64_e32 v[90:91], 0
	v_mov_b64_e32 v[92:93], 0
	v_mov_b64_e32 v[94:95], 0
	v_mov_b64_e32 v[96:97], 0
	v_mov_b64_e32 v[98:99], 0
	v_mov_b64_e32 v[100:101], 0
	v_mov_b64_e32 v[102:103], 0
	v_mov_b64_e32 v[104:105], 0
	v_mov_b64_e32 v[106:107], 0
	v_mov_b64_e32 v[108:109], 0
	v_mov_b64_e32 v[110:111], 0
	v_mov_b64_e32 v[112:113], 0
	v_mov_b64_e32 v[114:115], 0
	v_mov_b64_e32 v[116:117], 0
	v_mov_b64_e32 v[118:119], 0
	v_mov_b64_e32 v[120:121], 0
	v_mov_b64_e32 v[122:123], 0
	v_mov_b64_e32 v[124:125], 0
	v_mov_b64_e32 v[126:127], 0
	s_cmp_eq_u32 s100, 1
	s_cbranch_scc0 .Lgemm_nobar_121
	s_mov_b32 s100, 0
	s_barrier

.LBB0_197:
	s_add_u32 s56, s34, 0x100
	s_addc_u32 s57, s35, 0
	s_mov_b32 s58, -2
	v_mov_b64_e32 v[0:1], 0
	v_mov_b64_e32 v[2:3], 0
	v_mov_b64_e32 v[4:5], 0
	v_mov_b64_e32 v[6:7], 0
	v_mov_b64_e32 v[8:9], 0
	v_mov_b64_e32 v[10:11], 0
	v_mov_b64_e32 v[12:13], 0
	v_mov_b64_e32 v[14:15], 0
	v_mov_b64_e32 v[16:17], 0
	v_mov_b64_e32 v[18:19], 0
	v_mov_b64_e32 v[20:21], 0
	v_mov_b64_e32 v[22:23], 0
	v_mov_b64_e32 v[24:25], 0
	v_mov_b64_e32 v[26:27], 0
	v_mov_b64_e32 v[28:29], 0
	v_mov_b64_e32 v[30:31], 0
	v_mov_b64_e32 v[32:33], 0
	v_mov_b64_e32 v[34:35], 0
	v_mov_b64_e32 v[36:37], 0
	v_mov_b64_e32 v[38:39], 0
	v_mov_b64_e32 v[40:41], 0
	v_mov_b64_e32 v[42:43], 0
	v_mov_b64_e32 v[44:45], 0
	v_mov_b64_e32 v[46:47], 0
	v_mov_b64_e32 v[48:49], 0
	v_mov_b64_e32 v[50:51], 0
	v_mov_b64_e32 v[52:53], 0
	v_mov_b64_e32 v[54:55], 0
	v_mov_b64_e32 v[56:57], 0
	v_mov_b64_e32 v[58:59], 0
	v_mov_b64_e32 v[60:61], 0
	v_mov_b64_e32 v[62:63], 0
	v_mov_b64_e32 v[64:65], 0
	v_mov_b64_e32 v[66:67], 0
	v_mov_b64_e32 v[68:69], 0
	v_mov_b64_e32 v[70:71], 0
	v_mov_b64_e32 v[72:73], 0
	v_mov_b64_e32 v[74:75], 0
	v_mov_b64_e32 v[76:77], 0
	v_mov_b64_e32 v[78:79], 0
	v_mov_b64_e32 v[80:81], 0
	v_mov_b64_e32 v[82:83], 0
	v_mov_b64_e32 v[84:85], 0
	v_mov_b64_e32 v[86:87], 0
	v_mov_b64_e32 v[88:89], 0
	v_mov_b64_e32 v[90:91], 0
	v_mov_b64_e32 v[92:93], 0
	v_mov_b64_e32 v[94:95], 0
	v_mov_b64_e32 v[96:97], 0
	v_mov_b64_e32 v[98:99], 0
	v_mov_b64_e32 v[100:101], 0
	v_mov_b64_e32 v[102:103], 0
	v_mov_b64_e32 v[104:105], 0
	v_mov_b64_e32 v[106:107], 0
	v_mov_b64_e32 v[108:109], 0
	v_mov_b64_e32 v[110:111], 0
	v_mov_b64_e32 v[112:113], 0
	v_mov_b64_e32 v[114:115], 0
	v_mov_b64_e32 v[116:117], 0
	v_mov_b64_e32 v[118:119], 0
	v_mov_b64_e32 v[120:121], 0
	v_mov_b64_e32 v[122:123], 0
	v_mov_b64_e32 v[124:125], 0
	v_mov_b64_e32 v[126:127], 0
	s_cmp_eq_u32 s100, 1
	s_cbranch_scc0 .Lgemm_nobar_189
	s_mov_b32 s100, 0
	s_barrier

.LBB0_355:
	s_ashr_i32 s19, s18, 31
	s_lshl_b64 s[20:21], s[18:19], 19
	s_add_u32 s20, s0, s20
	s_addc_u32 s21, s1, s21
	s_and_b64 s[22:23], s[4:5], exec
	s_cselect_b32 s19, s21, s29
	s_cselect_b32 s45, s20, s28
	s_ashr_i32 s17, s16, 31
	s_lshl_b64 s[22:23], s[16:17], 19
	s_add_u32 s22, s6, s22
	s_addc_u32 s23, s7, s23
	s_and_b64 s[30:31], s[4:5], exec
	s_cselect_b32 s17, s23, s27
	s_cselect_b32 s46, s22, s26
	s_add_u32 s47, s26, 0x100
	s_addc_u32 s48, s27, 0
	s_add_u32 s26, s28, 0x40080
	s_addc_u32 s27, s29, 0
	s_mov_b32 s49, -2
	v_mov_b64_e32 v[0:1], 0
	v_mov_b64_e32 v[2:3], 0
	v_mov_b64_e32 v[4:5], 0
	v_mov_b64_e32 v[6:7], 0
	v_mov_b64_e32 v[8:9], 0
	v_mov_b64_e32 v[10:11], 0
	v_mov_b64_e32 v[12:13], 0
	v_mov_b64_e32 v[14:15], 0
	v_mov_b64_e32 v[16:17], 0
	v_mov_b64_e32 v[18:19], 0
	v_mov_b64_e32 v[20:21], 0
	v_mov_b64_e32 v[22:23], 0
	v_mov_b64_e32 v[24:25], 0
	v_mov_b64_e32 v[26:27], 0
	v_mov_b64_e32 v[28:29], 0
	v_mov_b64_e32 v[30:31], 0
	v_mov_b64_e32 v[32:33], 0
	v_mov_b64_e32 v[34:35], 0
	v_mov_b64_e32 v[36:37], 0
	v_mov_b64_e32 v[38:39], 0
	v_mov_b64_e32 v[40:41], 0
	v_mov_b64_e32 v[42:43], 0
	v_mov_b64_e32 v[44:45], 0
	v_mov_b64_e32 v[46:47], 0
	v_mov_b64_e32 v[48:49], 0
	v_mov_b64_e32 v[50:51], 0
	v_mov_b64_e32 v[52:53], 0
	v_mov_b64_e32 v[54:55], 0
	v_mov_b64_e32 v[56:57], 0
	v_mov_b64_e32 v[58:59], 0
	v_mov_b64_e32 v[60:61], 0
	v_mov_b64_e32 v[62:63], 0
	v_mov_b64_e32 v[64:65], 0
	v_mov_b64_e32 v[66:67], 0
	v_mov_b64_e32 v[68:69], 0
	v_mov_b64_e32 v[70:71], 0
	v_mov_b64_e32 v[72:73], 0
	v_mov_b64_e32 v[74:75], 0
	v_mov_b64_e32 v[76:77], 0
	v_mov_b64_e32 v[78:79], 0
	v_mov_b64_e32 v[80:81], 0
	v_mov_b64_e32 v[82:83], 0
	v_mov_b64_e32 v[84:85], 0
	v_mov_b64_e32 v[86:87], 0
	v_mov_b64_e32 v[88:89], 0
	v_mov_b64_e32 v[90:91], 0
	v_mov_b64_e32 v[92:93], 0
	v_mov_b64_e32 v[94:95], 0
	v_mov_b64_e32 v[96:97], 0
	v_mov_b64_e32 v[98:99], 0
	v_mov_b64_e32 v[100:101], 0
	v_mov_b64_e32 v[102:103], 0
	v_mov_b64_e32 v[104:105], 0
	v_mov_b64_e32 v[106:107], 0
	v_mov_b64_e32 v[108:109], 0
	v_mov_b64_e32 v[110:111], 0
	v_mov_b64_e32 v[112:113], 0
	v_mov_b64_e32 v[114:115], 0
	v_mov_b64_e32 v[116:117], 0
	v_mov_b64_e32 v[118:119], 0
	v_mov_b64_e32 v[120:121], 0
	v_mov_b64_e32 v[122:123], 0
	v_mov_b64_e32 v[124:125], 0
	v_mov_b64_e32 v[126:127], 0
	s_cmp_eq_u32 s100, 1
	s_cbranch_scc0 .Lgemm_nobar_351
	s_mov_b32 s100, 0
	s_barrier

.LBB0_728:
	s_ashr_i32 s27, s26, 31
	s_lshl_b64 s[28:29], s[26:27], 19
	s_add_u32 s28, s8, s28
	s_addc_u32 s29, s9, s29
	s_and_b64 s[30:31], s[6:7], exec
	s_cselect_b32 s27, s29, s37
	s_cselect_b32 s55, s28, s36
	s_ashr_i32 s25, s24, 31
	s_lshl_b64 s[30:31], s[24:25], 19
	s_add_u32 s30, s0, s30
	s_addc_u32 s31, s1, s31
	s_and_b64 s[38:39], s[6:7], exec
	s_cselect_b32 s25, s31, s35
	s_cselect_b32 s56, s30, s34
	s_add_u32 s57, s34, 0x100
	s_addc_u32 s58, s35, 0
	s_add_u32 s34, s36, 0x40080
	s_addc_u32 s35, s37, 0
	s_mov_b32 s59, -2
	v_mov_b64_e32 v[0:1], 0
	v_mov_b64_e32 v[2:3], 0
	v_mov_b64_e32 v[4:5], 0
	v_mov_b64_e32 v[6:7], 0
	v_mov_b64_e32 v[8:9], 0
	v_mov_b64_e32 v[10:11], 0
	v_mov_b64_e32 v[12:13], 0
	v_mov_b64_e32 v[14:15], 0
	v_mov_b64_e32 v[16:17], 0
	v_mov_b64_e32 v[18:19], 0
	v_mov_b64_e32 v[20:21], 0
	v_mov_b64_e32 v[22:23], 0
	v_mov_b64_e32 v[24:25], 0
	v_mov_b64_e32 v[26:27], 0
	v_mov_b64_e32 v[28:29], 0
	v_mov_b64_e32 v[30:31], 0
	v_mov_b64_e32 v[32:33], 0
	v_mov_b64_e32 v[34:35], 0
	v_mov_b64_e32 v[36:37], 0
	v_mov_b64_e32 v[38:39], 0
	v_mov_b64_e32 v[40:41], 0
	v_mov_b64_e32 v[42:43], 0
	v_mov_b64_e32 v[44:45], 0
	v_mov_b64_e32 v[46:47], 0
	v_mov_b64_e32 v[48:49], 0
	v_mov_b64_e32 v[50:51], 0
	v_mov_b64_e32 v[52:53], 0
	v_mov_b64_e32 v[54:55], 0
	v_mov_b64_e32 v[56:57], 0
	v_mov_b64_e32 v[58:59], 0
	v_mov_b64_e32 v[60:61], 0
	v_mov_b64_e32 v[62:63], 0
	v_mov_b64_e32 v[64:65], 0
	v_mov_b64_e32 v[66:67], 0
	v_mov_b64_e32 v[68:69], 0
	v_mov_b64_e32 v[70:71], 0
	v_mov_b64_e32 v[72:73], 0
	v_mov_b64_e32 v[74:75], 0
	v_mov_b64_e32 v[76:77], 0
	v_mov_b64_e32 v[78:79], 0
	v_mov_b64_e32 v[80:81], 0
	v_mov_b64_e32 v[82:83], 0
	v_mov_b64_e32 v[84:85], 0
	v_mov_b64_e32 v[86:87], 0
	v_mov_b64_e32 v[88:89], 0
	v_mov_b64_e32 v[90:91], 0
	v_mov_b64_e32 v[92:93], 0
	v_mov_b64_e32 v[94:95], 0
	v_mov_b64_e32 v[96:97], 0
	v_mov_b64_e32 v[98:99], 0
	v_mov_b64_e32 v[100:101], 0
	v_mov_b64_e32 v[102:103], 0
	v_mov_b64_e32 v[104:105], 0
	v_mov_b64_e32 v[106:107], 0
	v_mov_b64_e32 v[108:109], 0
	v_mov_b64_e32 v[110:111], 0
	v_mov_b64_e32 v[112:113], 0
	v_mov_b64_e32 v[114:115], 0
	v_mov_b64_e32 v[116:117], 0
	v_mov_b64_e32 v[118:119], 0
	v_mov_b64_e32 v[120:121], 0
	v_mov_b64_e32 v[122:123], 0
	v_mov_b64_e32 v[124:125], 0
	v_mov_b64_e32 v[126:127], 0
	s_cmp_eq_u32 s100, 1
	s_cbranch_scc0 .Lgemm_nobar_724
	s_mov_b32 s100, 0
	s_barrier

.LBB0_876:
	s_ashr_i32 s19, s18, 31
	s_lshl_b64 s[20:21], s[18:19], 19
	s_add_u32 s20, s0, s20
	s_addc_u32 s21, s1, s21
	s_and_b64 s[22:23], s[6:7], exec
	s_cselect_b32 s19, s21, s27
	s_cselect_b32 s45, s20, s26
	s_ashr_i32 s17, s16, 31
	s_lshl_b64 s[22:23], s[16:17], 19
	s_add_u32 s22, s4, s22
	s_addc_u32 s23, s5, s23
	s_and_b64 s[28:29], s[6:7], exec
	s_cselect_b32 s17, s23, s25
	s_cselect_b32 s46, s22, s24
	s_add_u32 s47, s24, 0x100
	s_addc_u32 s48, s25, 0
	s_add_u32 s24, s26, 0x40080
	s_addc_u32 s25, s27, 0
	s_mov_b32 s49, -2
	v_mov_b64_e32 v[0:1], 0
	v_mov_b64_e32 v[2:3], 0
	v_mov_b64_e32 v[4:5], 0
	v_mov_b64_e32 v[6:7], 0
	v_mov_b64_e32 v[8:9], 0
	v_mov_b64_e32 v[10:11], 0
	v_mov_b64_e32 v[12:13], 0
	v_mov_b64_e32 v[14:15], 0
	v_mov_b64_e32 v[16:17], 0
	v_mov_b64_e32 v[18:19], 0
	v_mov_b64_e32 v[20:21], 0
	v_mov_b64_e32 v[22:23], 0
	v_mov_b64_e32 v[24:25], 0
	v_mov_b64_e32 v[26:27], 0
	v_mov_b64_e32 v[28:29], 0
	v_mov_b64_e32 v[30:31], 0
	v_mov_b64_e32 v[32:33], 0
	v_mov_b64_e32 v[34:35], 0
	v_mov_b64_e32 v[36:37], 0
	v_mov_b64_e32 v[38:39], 0
	v_mov_b64_e32 v[40:41], 0
	v_mov_b64_e32 v[42:43], 0
	v_mov_b64_e32 v[44:45], 0
	v_mov_b64_e32 v[46:47], 0
	v_mov_b64_e32 v[48:49], 0
	v_mov_b64_e32 v[50:51], 0
	v_mov_b64_e32 v[52:53], 0
	v_mov_b64_e32 v[54:55], 0
	v_mov_b64_e32 v[56:57], 0
	v_mov_b64_e32 v[58:59], 0
	v_mov_b64_e32 v[60:61], 0
	v_mov_b64_e32 v[62:63], 0
	v_mov_b64_e32 v[64:65], 0
	v_mov_b64_e32 v[66:67], 0
	v_mov_b64_e32 v[68:69], 0
	v_mov_b64_e32 v[70:71], 0
	v_mov_b64_e32 v[72:73], 0
	v_mov_b64_e32 v[74:75], 0
	v_mov_b64_e32 v[76:77], 0
	v_mov_b64_e32 v[78:79], 0
	v_mov_b64_e32 v[80:81], 0
	v_mov_b64_e32 v[82:83], 0
	v_mov_b64_e32 v[84:85], 0
	v_mov_b64_e32 v[86:87], 0
	v_mov_b64_e32 v[88:89], 0
	v_mov_b64_e32 v[90:91], 0
	v_mov_b64_e32 v[92:93], 0
	v_mov_b64_e32 v[94:95], 0
	v_mov_b64_e32 v[96:97], 0
	v_mov_b64_e32 v[98:99], 0
	v_mov_b64_e32 v[100:101], 0
	v_mov_b64_e32 v[102:103], 0
	v_mov_b64_e32 v[104:105], 0
	v_mov_b64_e32 v[106:107], 0
	v_mov_b64_e32 v[108:109], 0
	v_mov_b64_e32 v[110:111], 0
	v_mov_b64_e32 v[112:113], 0
	v_mov_b64_e32 v[114:115], 0
	v_mov_b64_e32 v[116:117], 0
	v_mov_b64_e32 v[118:119], 0
	v_mov_b64_e32 v[120:121], 0
	v_mov_b64_e32 v[122:123], 0
	v_mov_b64_e32 v[124:125], 0
	v_mov_b64_e32 v[126:127], 0
	s_cmp_eq_u32 s100, 1
	s_cbranch_scc0 .Lgemm_nobar_872
	s_mov_b32 s100, 0
	s_barrier

.LBB0_948:
	s_add_u32 s57, s34, 0x100
	s_addc_u32 s58, s35, 0
	s_mov_b32 s59, -2
	v_mov_b64_e32 v[0:1], 0
	v_mov_b64_e32 v[2:3], 0
	v_mov_b64_e32 v[4:5], 0
	v_mov_b64_e32 v[6:7], 0
	v_mov_b64_e32 v[8:9], 0
	v_mov_b64_e32 v[10:11], 0
	v_mov_b64_e32 v[12:13], 0
	v_mov_b64_e32 v[14:15], 0
	v_mov_b64_e32 v[16:17], 0
	v_mov_b64_e32 v[18:19], 0
	v_mov_b64_e32 v[20:21], 0
	v_mov_b64_e32 v[22:23], 0
	v_mov_b64_e32 v[24:25], 0
	v_mov_b64_e32 v[26:27], 0
	v_mov_b64_e32 v[28:29], 0
	v_mov_b64_e32 v[30:31], 0
	v_mov_b64_e32 v[32:33], 0
	v_mov_b64_e32 v[34:35], 0
	v_mov_b64_e32 v[36:37], 0
	v_mov_b64_e32 v[38:39], 0
	v_mov_b64_e32 v[40:41], 0
	v_mov_b64_e32 v[42:43], 0
	v_mov_b64_e32 v[44:45], 0
	v_mov_b64_e32 v[46:47], 0
	v_mov_b64_e32 v[48:49], 0
	v_mov_b64_e32 v[50:51], 0
	v_mov_b64_e32 v[52:53], 0
	v_mov_b64_e32 v[54:55], 0
	v_mov_b64_e32 v[56:57], 0
	v_mov_b64_e32 v[58:59], 0
	v_mov_b64_e32 v[60:61], 0
	v_mov_b64_e32 v[62:63], 0
	v_mov_b64_e32 v[64:65], 0
	v_mov_b64_e32 v[66:67], 0
	v_mov_b64_e32 v[68:69], 0
	v_mov_b64_e32 v[70:71], 0
	v_mov_b64_e32 v[72:73], 0
	v_mov_b64_e32 v[74:75], 0
	v_mov_b64_e32 v[76:77], 0
	v_mov_b64_e32 v[78:79], 0
	v_mov_b64_e32 v[80:81], 0
	v_mov_b64_e32 v[82:83], 0
	v_mov_b64_e32 v[84:85], 0
	v_mov_b64_e32 v[86:87], 0
	v_mov_b64_e32 v[88:89], 0
	v_mov_b64_e32 v[90:91], 0
	v_mov_b64_e32 v[92:93], 0
	v_mov_b64_e32 v[94:95], 0
	v_mov_b64_e32 v[96:97], 0
	v_mov_b64_e32 v[98:99], 0
	v_mov_b64_e32 v[100:101], 0
	v_mov_b64_e32 v[102:103], 0
	v_mov_b64_e32 v[104:105], 0
	v_mov_b64_e32 v[106:107], 0
	v_mov_b64_e32 v[108:109], 0
	v_mov_b64_e32 v[110:111], 0
	v_mov_b64_e32 v[112:113], 0
	v_mov_b64_e32 v[114:115], 0
	v_mov_b64_e32 v[116:117], 0
	v_mov_b64_e32 v[118:119], 0
	v_mov_b64_e32 v[120:121], 0
	v_mov_b64_e32 v[122:123], 0
	v_mov_b64_e32 v[124:125], 0
	v_mov_b64_e32 v[126:127], 0
	s_cmp_eq_u32 s100, 1
	s_cbranch_scc0 .Lgemm_nobar_940
	s_mov_b32 s100, 0
	s_barrier

.LBB0_1110:
	s_ashr_i32 s31, s30, 31
	s_lshl_b64 s[34:35], s[30:31], 19
	s_add_u32 s34, s10, s34
	s_addc_u32 s35, s11, s35
	s_and_b64 s[36:37], s[8:9], exec
	s_cselect_b32 s31, s35, s43
	s_cselect_b32 s59, s34, s42
	s_ashr_i32 s29, s28, 31
	s_lshl_b64 s[36:37], s[28:29], 19
	s_add_u32 s36, s12, s36
	s_addc_u32 s37, s13, s37
	s_and_b64 s[44:45], s[8:9], exec
	s_cselect_b32 s29, s37, s41
	s_cselect_b32 s60, s36, s40
	s_add_u32 s61, s40, 0x100
	s_addc_u32 s62, s41, 0
	s_add_u32 s40, s42, 0x40080
	s_addc_u32 s41, s43, 0
	s_mov_b32 s63, -2
	v_mov_b64_e32 v[0:1], 0
	v_mov_b64_e32 v[2:3], 0
	v_mov_b64_e32 v[4:5], 0
	v_mov_b64_e32 v[6:7], 0
	v_mov_b64_e32 v[8:9], 0
	v_mov_b64_e32 v[10:11], 0
	v_mov_b64_e32 v[12:13], 0
	v_mov_b64_e32 v[14:15], 0
	v_mov_b64_e32 v[16:17], 0
	v_mov_b64_e32 v[18:19], 0
	v_mov_b64_e32 v[20:21], 0
	v_mov_b64_e32 v[22:23], 0
	v_mov_b64_e32 v[24:25], 0
	v_mov_b64_e32 v[26:27], 0
	v_mov_b64_e32 v[28:29], 0
	v_mov_b64_e32 v[30:31], 0
	v_mov_b64_e32 v[32:33], 0
	v_mov_b64_e32 v[34:35], 0
	v_mov_b64_e32 v[36:37], 0
	v_mov_b64_e32 v[38:39], 0
	v_mov_b64_e32 v[40:41], 0
	v_mov_b64_e32 v[42:43], 0
	v_mov_b64_e32 v[44:45], 0
	v_mov_b64_e32 v[46:47], 0
	v_mov_b64_e32 v[48:49], 0
	v_mov_b64_e32 v[50:51], 0
	v_mov_b64_e32 v[52:53], 0
	v_mov_b64_e32 v[54:55], 0
	v_mov_b64_e32 v[56:57], 0
	v_mov_b64_e32 v[58:59], 0
	v_mov_b64_e32 v[60:61], 0
	v_mov_b64_e32 v[62:63], 0
	v_mov_b64_e32 v[64:65], 0
	v_mov_b64_e32 v[66:67], 0
	v_mov_b64_e32 v[68:69], 0
	v_mov_b64_e32 v[70:71], 0
	v_mov_b64_e32 v[72:73], 0
	v_mov_b64_e32 v[74:75], 0
	v_mov_b64_e32 v[76:77], 0
	v_mov_b64_e32 v[78:79], 0
	v_mov_b64_e32 v[80:81], 0
	v_mov_b64_e32 v[82:83], 0
	v_mov_b64_e32 v[84:85], 0
	v_mov_b64_e32 v[86:87], 0
	v_mov_b64_e32 v[88:89], 0
	v_mov_b64_e32 v[90:91], 0
	v_mov_b64_e32 v[92:93], 0
	v_mov_b64_e32 v[94:95], 0
	v_mov_b64_e32 v[96:97], 0
	v_mov_b64_e32 v[98:99], 0
	v_mov_b64_e32 v[100:101], 0
	v_mov_b64_e32 v[102:103], 0
	v_mov_b64_e32 v[104:105], 0
	v_mov_b64_e32 v[106:107], 0
	v_mov_b64_e32 v[108:109], 0
	v_mov_b64_e32 v[110:111], 0
	v_mov_b64_e32 v[112:113], 0
	v_mov_b64_e32 v[114:115], 0
	v_mov_b64_e32 v[116:117], 0
	v_mov_b64_e32 v[118:119], 0
	v_mov_b64_e32 v[120:121], 0
	v_mov_b64_e32 v[122:123], 0
	v_mov_b64_e32 v[124:125], 0
	v_mov_b64_e32 v[126:127], 0
	s_cmp_eq_u32 s100, 1
	s_cbranch_scc0 .Lgemm_nobar_1102
	s_mov_b32 s100, 0
	s_barrier

.LBB0_1280:
	s_ashr_i32 s21, s20, 31
	s_lshl_b64 s[22:23], s[20:21], 19
	s_add_u32 s22, s0, s22
	s_addc_u32 s23, s1, s23
	s_and_b64 s[24:25], s[8:9], exec
	s_cselect_b32 s21, s23, s29
	s_cselect_b32 s47, s22, s28
	s_ashr_i32 s19, s18, 31
	s_lshl_b64 s[24:25], s[18:19], 19
	s_add_u32 s24, s4, s24
	s_addc_u32 s25, s5, s25
	s_and_b64 s[30:31], s[8:9], exec
	s_cselect_b32 s19, s25, s27
	s_cselect_b32 s48, s24, s26
	s_add_u32 s49, s26, 0x100
	s_addc_u32 s50, s27, 0
	s_add_u32 s26, s28, 0x40080
	s_addc_u32 s27, s29, 0
	s_mov_b32 s51, -2
	v_mov_b64_e32 v[0:1], 0
	v_mov_b64_e32 v[2:3], 0
	v_mov_b64_e32 v[4:5], 0
	v_mov_b64_e32 v[6:7], 0
	v_mov_b64_e32 v[8:9], 0
	v_mov_b64_e32 v[10:11], 0
	v_mov_b64_e32 v[12:13], 0
	v_mov_b64_e32 v[14:15], 0
	v_mov_b64_e32 v[16:17], 0
	v_mov_b64_e32 v[18:19], 0
	v_mov_b64_e32 v[20:21], 0
	v_mov_b64_e32 v[22:23], 0
	v_mov_b64_e32 v[24:25], 0
	v_mov_b64_e32 v[26:27], 0
	v_mov_b64_e32 v[28:29], 0
	v_mov_b64_e32 v[30:31], 0
	v_mov_b64_e32 v[32:33], 0
	v_mov_b64_e32 v[34:35], 0
	v_mov_b64_e32 v[36:37], 0
	v_mov_b64_e32 v[38:39], 0
	v_mov_b64_e32 v[40:41], 0
	v_mov_b64_e32 v[42:43], 0
	v_mov_b64_e32 v[44:45], 0
	v_mov_b64_e32 v[46:47], 0
	v_mov_b64_e32 v[48:49], 0
	v_mov_b64_e32 v[50:51], 0
	v_mov_b64_e32 v[52:53], 0
	v_mov_b64_e32 v[54:55], 0
	v_mov_b64_e32 v[56:57], 0
	v_mov_b64_e32 v[58:59], 0
	v_mov_b64_e32 v[60:61], 0
	v_mov_b64_e32 v[62:63], 0
	v_mov_b64_e32 v[64:65], 0
	v_mov_b64_e32 v[66:67], 0
	v_mov_b64_e32 v[68:69], 0
	v_mov_b64_e32 v[70:71], 0
	v_mov_b64_e32 v[72:73], 0
	v_mov_b64_e32 v[74:75], 0
	v_mov_b64_e32 v[76:77], 0
	v_mov_b64_e32 v[78:79], 0
	v_mov_b64_e32 v[80:81], 0
	v_mov_b64_e32 v[82:83], 0
	v_mov_b64_e32 v[84:85], 0
	v_mov_b64_e32 v[86:87], 0
	v_mov_b64_e32 v[88:89], 0
	v_mov_b64_e32 v[90:91], 0
	v_mov_b64_e32 v[92:93], 0
	v_mov_b64_e32 v[94:95], 0
	v_mov_b64_e32 v[96:97], 0
	v_mov_b64_e32 v[98:99], 0
	v_mov_b64_e32 v[100:101], 0
	v_mov_b64_e32 v[102:103], 0
	v_mov_b64_e32 v[104:105], 0
	v_mov_b64_e32 v[106:107], 0
	v_mov_b64_e32 v[108:109], 0
	v_mov_b64_e32 v[110:111], 0
	v_mov_b64_e32 v[112:113], 0
	v_mov_b64_e32 v[114:115], 0
	v_mov_b64_e32 v[116:117], 0
	v_mov_b64_e32 v[118:119], 0
	v_mov_b64_e32 v[120:121], 0
	v_mov_b64_e32 v[122:123], 0
	v_mov_b64_e32 v[124:125], 0
	v_mov_b64_e32 v[126:127], 0
	s_cmp_eq_u32 s100, 1
	s_cbranch_scc0 .Lgemm_nobar_1276
	s_mov_b32 s100, 0
	s_barrier

.LBB0_1512:
	s_ashr_i32 s31, s30, 31
	s_lshl_b64 s[34:35], s[30:31], 19
	s_add_u32 s34, s4, s34
	s_addc_u32 s35, s5, s35
	s_and_b64 s[36:37], s[8:9], exec
	s_cselect_b32 s31, s35, s41
	s_cselect_b32 s59, s34, s40
	s_ashr_i32 s29, s28, 31
	s_lshl_b64 s[36:37], s[28:29], 19
	s_add_u32 s36, s10, s36
	s_addc_u32 s37, s11, s37
	s_and_b64 s[42:43], s[8:9], exec
	s_cselect_b32 s29, s37, s39
	s_cselect_b32 s60, s36, s38
	s_add_u32 s61, s38, 0x100
	s_addc_u32 s62, s39, 0
	s_add_u32 s38, s40, 0x40080
	s_addc_u32 s39, s41, 0
	s_mov_b32 s63, -2
	v_mov_b64_e32 v[0:1], 0
	v_mov_b64_e32 v[2:3], 0
	v_mov_b64_e32 v[4:5], 0
	v_mov_b64_e32 v[6:7], 0
	v_mov_b64_e32 v[8:9], 0
	v_mov_b64_e32 v[10:11], 0
	v_mov_b64_e32 v[12:13], 0
	v_mov_b64_e32 v[14:15], 0
	v_mov_b64_e32 v[16:17], 0
	v_mov_b64_e32 v[18:19], 0
	v_mov_b64_e32 v[20:21], 0
	v_mov_b64_e32 v[22:23], 0
	v_mov_b64_e32 v[24:25], 0
	v_mov_b64_e32 v[26:27], 0
	v_mov_b64_e32 v[28:29], 0
	v_mov_b64_e32 v[30:31], 0
	v_mov_b64_e32 v[32:33], 0
	v_mov_b64_e32 v[34:35], 0
	v_mov_b64_e32 v[36:37], 0
	v_mov_b64_e32 v[38:39], 0
	v_mov_b64_e32 v[40:41], 0
	v_mov_b64_e32 v[42:43], 0
	v_mov_b64_e32 v[44:45], 0
	v_mov_b64_e32 v[46:47], 0
	v_mov_b64_e32 v[48:49], 0
	v_mov_b64_e32 v[50:51], 0
	v_mov_b64_e32 v[52:53], 0
	v_mov_b64_e32 v[54:55], 0
	v_mov_b64_e32 v[56:57], 0
	v_mov_b64_e32 v[58:59], 0
	v_mov_b64_e32 v[60:61], 0
	v_mov_b64_e32 v[62:63], 0
	v_mov_b64_e32 v[64:65], 0
	v_mov_b64_e32 v[66:67], 0
	v_mov_b64_e32 v[68:69], 0
	v_mov_b64_e32 v[70:71], 0
	v_mov_b64_e32 v[72:73], 0
	v_mov_b64_e32 v[74:75], 0
	v_mov_b64_e32 v[76:77], 0
	v_mov_b64_e32 v[78:79], 0
	v_mov_b64_e32 v[80:81], 0
	v_mov_b64_e32 v[82:83], 0
	v_mov_b64_e32 v[84:85], 0
	v_mov_b64_e32 v[86:87], 0
	v_mov_b64_e32 v[88:89], 0
	v_mov_b64_e32 v[90:91], 0
	v_mov_b64_e32 v[92:93], 0
	v_mov_b64_e32 v[94:95], 0
	v_mov_b64_e32 v[96:97], 0
	v_mov_b64_e32 v[98:99], 0
	v_mov_b64_e32 v[100:101], 0
	v_mov_b64_e32 v[102:103], 0
	v_mov_b64_e32 v[104:105], 0
	v_mov_b64_e32 v[106:107], 0
	v_mov_b64_e32 v[108:109], 0
	v_mov_b64_e32 v[110:111], 0
	v_mov_b64_e32 v[112:113], 0
	v_mov_b64_e32 v[114:115], 0
	v_mov_b64_e32 v[116:117], 0
	v_mov_b64_e32 v[118:119], 0
	v_mov_b64_e32 v[120:121], 0
	v_mov_b64_e32 v[122:123], 0
	v_mov_b64_e32 v[124:125], 0
	v_mov_b64_e32 v[126:127], 0
	s_cmp_eq_u32 s100, 1
	s_cbranch_scc0 .Lgemm_nobar_1508
	s_mov_b32 s100, 0
	s_barrier

.LBB0_1528:
	s_ashr_i32 s31, s30, 31
	s_lshl_b64 s[34:35], s[30:31], 19
	s_add_u32 s34, s4, s34
	s_addc_u32 s35, s5, s35
	s_and_b64 s[36:37], s[8:9], exec
	s_cselect_b32 s31, s35, s41
	s_cselect_b32 s58, s34, s40
	s_ashr_i32 s29, s28, 31
	s_lshl_b64 s[36:37], s[28:29], 19
	s_add_u32 s36, s10, s36
	s_addc_u32 s37, s11, s37
	s_and_b64 s[42:43], s[8:9], exec
	s_cselect_b32 s29, s37, s39
	s_cselect_b32 s59, s36, s38
	s_add_u32 s60, s38, 0x100
	s_addc_u32 s61, s39, 0
	s_add_u32 s38, s40, 0x40080
	s_addc_u32 s39, s41, 0
	s_mov_b32 s62, -2
	v_mov_b64_e32 v[0:1], 0
	v_mov_b64_e32 v[2:3], 0
	v_mov_b64_e32 v[4:5], 0
	v_mov_b64_e32 v[6:7], 0
	v_mov_b64_e32 v[8:9], 0
	v_mov_b64_e32 v[10:11], 0
	v_mov_b64_e32 v[12:13], 0
	v_mov_b64_e32 v[14:15], 0
	v_mov_b64_e32 v[16:17], 0
	v_mov_b64_e32 v[18:19], 0
	v_mov_b64_e32 v[20:21], 0
	v_mov_b64_e32 v[22:23], 0
	v_mov_b64_e32 v[24:25], 0
	v_mov_b64_e32 v[26:27], 0
	v_mov_b64_e32 v[28:29], 0
	v_mov_b64_e32 v[30:31], 0
	v_mov_b64_e32 v[32:33], 0
	v_mov_b64_e32 v[34:35], 0
	v_mov_b64_e32 v[36:37], 0
	v_mov_b64_e32 v[38:39], 0
	v_mov_b64_e32 v[40:41], 0
	v_mov_b64_e32 v[42:43], 0
	v_mov_b64_e32 v[44:45], 0
	v_mov_b64_e32 v[46:47], 0
	v_mov_b64_e32 v[48:49], 0
	v_mov_b64_e32 v[50:51], 0
	v_mov_b64_e32 v[52:53], 0
	v_mov_b64_e32 v[54:55], 0
	v_mov_b64_e32 v[56:57], 0
	v_mov_b64_e32 v[58:59], 0
	v_mov_b64_e32 v[60:61], 0
	v_mov_b64_e32 v[62:63], 0
	v_mov_b64_e32 v[64:65], 0
	v_mov_b64_e32 v[66:67], 0
	v_mov_b64_e32 v[68:69], 0
	v_mov_b64_e32 v[70:71], 0
	v_mov_b64_e32 v[72:73], 0
	v_mov_b64_e32 v[74:75], 0
	v_mov_b64_e32 v[76:77], 0
	v_mov_b64_e32 v[78:79], 0
	v_mov_b64_e32 v[80:81], 0
	v_mov_b64_e32 v[82:83], 0
	v_mov_b64_e32 v[84:85], 0
	v_mov_b64_e32 v[86:87], 0
	v_mov_b64_e32 v[88:89], 0
	v_mov_b64_e32 v[90:91], 0
	v_mov_b64_e32 v[92:93], 0
	v_mov_b64_e32 v[94:95], 0
	v_mov_b64_e32 v[96:97], 0
	v_mov_b64_e32 v[98:99], 0
	v_mov_b64_e32 v[100:101], 0
	v_mov_b64_e32 v[102:103], 0
	v_mov_b64_e32 v[104:105], 0
	v_mov_b64_e32 v[106:107], 0
	v_mov_b64_e32 v[108:109], 0
	v_mov_b64_e32 v[110:111], 0
	v_mov_b64_e32 v[112:113], 0
	v_mov_b64_e32 v[114:115], 0
	v_mov_b64_e32 v[116:117], 0
	v_mov_b64_e32 v[118:119], 0
	v_mov_b64_e32 v[120:121], 0
	v_mov_b64_e32 v[122:123], 0
	v_mov_b64_e32 v[124:125], 0
	v_mov_b64_e32 v[126:127], 0
	s_cmp_eq_u32 s100, 1
	s_cbranch_scc0 .Lgemm_nobar_1524
	s_mov_b32 s100, 0
	s_barrier

.LBB0_1800:
	s_ashr_i32 s29, s28, 31
	s_lshl_b64 s[30:31], s[28:29], 19
	s_add_u32 s30, s0, s30
	s_addc_u32 s31, s1, s31
	s_and_b64 s[34:35], s[8:9], exec
	s_cselect_b32 s29, s31, s39
	s_cselect_b32 s57, s30, s38
	s_ashr_i32 s27, s26, 31
	s_lshl_b64 s[34:35], s[26:27], 19
	s_add_u32 s34, s4, s34
	s_addc_u32 s35, s5, s35
	s_and_b64 s[40:41], s[8:9], exec
	s_cselect_b32 s27, s35, s37
	s_cselect_b32 s58, s34, s36
	s_add_u32 s59, s36, 0x100
	s_addc_u32 s60, s37, 0
	s_add_u32 s36, s38, 0x40080
	s_addc_u32 s37, s39, 0
	s_mov_b32 s61, -2
	v_mov_b64_e32 v[0:1], 0
	v_mov_b64_e32 v[2:3], 0
	v_mov_b64_e32 v[4:5], 0
	v_mov_b64_e32 v[6:7], 0
	v_mov_b64_e32 v[8:9], 0
	v_mov_b64_e32 v[10:11], 0
	v_mov_b64_e32 v[12:13], 0
	v_mov_b64_e32 v[14:15], 0
	v_mov_b64_e32 v[16:17], 0
	v_mov_b64_e32 v[18:19], 0
	v_mov_b64_e32 v[20:21], 0
	v_mov_b64_e32 v[22:23], 0
	v_mov_b64_e32 v[24:25], 0
	v_mov_b64_e32 v[26:27], 0
	v_mov_b64_e32 v[28:29], 0
	v_mov_b64_e32 v[30:31], 0
	v_mov_b64_e32 v[32:33], 0
	v_mov_b64_e32 v[34:35], 0
	v_mov_b64_e32 v[36:37], 0
	v_mov_b64_e32 v[38:39], 0
	v_mov_b64_e32 v[40:41], 0
	v_mov_b64_e32 v[42:43], 0
	v_mov_b64_e32 v[44:45], 0
	v_mov_b64_e32 v[46:47], 0
	v_mov_b64_e32 v[48:49], 0
	v_mov_b64_e32 v[50:51], 0
	v_mov_b64_e32 v[52:53], 0
	v_mov_b64_e32 v[54:55], 0
	v_mov_b64_e32 v[56:57], 0
	v_mov_b64_e32 v[58:59], 0
	v_mov_b64_e32 v[60:61], 0
	v_mov_b64_e32 v[62:63], 0
	v_mov_b64_e32 v[64:65], 0
	v_mov_b64_e32 v[66:67], 0
	v_mov_b64_e32 v[68:69], 0
	v_mov_b64_e32 v[70:71], 0
	v_mov_b64_e32 v[72:73], 0
	v_mov_b64_e32 v[74:75], 0
	v_mov_b64_e32 v[76:77], 0
	v_mov_b64_e32 v[78:79], 0
	v_mov_b64_e32 v[80:81], 0
	v_mov_b64_e32 v[82:83], 0
	v_mov_b64_e32 v[84:85], 0
	v_mov_b64_e32 v[86:87], 0
	v_mov_b64_e32 v[88:89], 0
	v_mov_b64_e32 v[90:91], 0
	v_mov_b64_e32 v[92:93], 0
	v_mov_b64_e32 v[94:95], 0
	v_mov_b64_e32 v[96:97], 0
	v_mov_b64_e32 v[98:99], 0
	v_mov_b64_e32 v[100:101], 0
	v_mov_b64_e32 v[102:103], 0
	v_mov_b64_e32 v[104:105], 0
	v_mov_b64_e32 v[106:107], 0
	v_mov_b64_e32 v[108:109], 0
	v_mov_b64_e32 v[110:111], 0
	v_mov_b64_e32 v[112:113], 0
	v_mov_b64_e32 v[114:115], 0
	v_mov_b64_e32 v[116:117], 0
	v_mov_b64_e32 v[118:119], 0
	v_mov_b64_e32 v[120:121], 0
	v_mov_b64_e32 v[122:123], 0
	v_mov_b64_e32 v[124:125], 0
	v_mov_b64_e32 v[126:127], 0
	s_cmp_eq_u32 s100, 1
	s_cbranch_scc0 .Lgemm_nobar_1796
	s_mov_b32 s100, 0
	s_barrier

.LBB0_1948:
	s_ashr_i32 s21, s20, 31
	s_lshl_b64 s[22:23], s[20:21], 19
	s_add_u32 s22, s0, s22
	s_addc_u32 s23, s1, s23
	s_and_b64 s[24:25], s[8:9], exec
	s_cselect_b32 s21, s23, s29
	s_cselect_b32 s45, s22, s28
	s_ashr_i32 s19, s18, 31
	s_lshl_b64 s[24:25], s[18:19], 19
	s_add_u32 s24, s4, s24
	s_addc_u32 s25, s5, s25
	s_and_b64 s[30:31], s[8:9], exec
	s_cselect_b32 s19, s25, s27
	s_cselect_b32 s46, s24, s26
	s_add_u32 s47, s26, 0x100
	s_addc_u32 s48, s27, 0
	s_add_u32 s26, s28, 0x40080
	s_addc_u32 s27, s29, 0
	s_mov_b32 s49, -2
	v_mov_b64_e32 v[0:1], 0
	v_mov_b64_e32 v[2:3], 0
	v_mov_b64_e32 v[4:5], 0
	v_mov_b64_e32 v[6:7], 0
	v_mov_b64_e32 v[8:9], 0
	v_mov_b64_e32 v[10:11], 0
	v_mov_b64_e32 v[12:13], 0
	v_mov_b64_e32 v[14:15], 0
	v_mov_b64_e32 v[16:17], 0
	v_mov_b64_e32 v[18:19], 0
	v_mov_b64_e32 v[20:21], 0
	v_mov_b64_e32 v[22:23], 0
	v_mov_b64_e32 v[24:25], 0
	v_mov_b64_e32 v[26:27], 0
	v_mov_b64_e32 v[28:29], 0
	v_mov_b64_e32 v[30:31], 0
	v_mov_b64_e32 v[32:33], 0
	v_mov_b64_e32 v[34:35], 0
	v_mov_b64_e32 v[36:37], 0
	v_mov_b64_e32 v[38:39], 0
	v_mov_b64_e32 v[40:41], 0
	v_mov_b64_e32 v[42:43], 0
	v_mov_b64_e32 v[44:45], 0
	v_mov_b64_e32 v[46:47], 0
	v_mov_b64_e32 v[48:49], 0
	v_mov_b64_e32 v[50:51], 0
	v_mov_b64_e32 v[52:53], 0
	v_mov_b64_e32 v[54:55], 0
	v_mov_b64_e32 v[56:57], 0
	v_mov_b64_e32 v[58:59], 0
	v_mov_b64_e32 v[60:61], 0
	v_mov_b64_e32 v[62:63], 0
	v_mov_b64_e32 v[64:65], 0
	v_mov_b64_e32 v[66:67], 0
	v_mov_b64_e32 v[68:69], 0
	v_mov_b64_e32 v[70:71], 0
	v_mov_b64_e32 v[72:73], 0
	v_mov_b64_e32 v[74:75], 0
	v_mov_b64_e32 v[76:77], 0
	v_mov_b64_e32 v[78:79], 0
	v_mov_b64_e32 v[80:81], 0
	v_mov_b64_e32 v[82:83], 0
	v_mov_b64_e32 v[84:85], 0
	v_mov_b64_e32 v[86:87], 0
	v_mov_b64_e32 v[88:89], 0
	v_mov_b64_e32 v[90:91], 0
	v_mov_b64_e32 v[92:93], 0
	v_mov_b64_e32 v[94:95], 0
	v_mov_b64_e32 v[96:97], 0
	v_mov_b64_e32 v[98:99], 0
	v_mov_b64_e32 v[100:101], 0
	v_mov_b64_e32 v[102:103], 0
	v_mov_b64_e32 v[104:105], 0
	v_mov_b64_e32 v[106:107], 0
	v_mov_b64_e32 v[108:109], 0
	v_mov_b64_e32 v[110:111], 0
	v_mov_b64_e32 v[112:113], 0
	v_mov_b64_e32 v[114:115], 0
	v_mov_b64_e32 v[116:117], 0
	v_mov_b64_e32 v[118:119], 0
	v_mov_b64_e32 v[120:121], 0
	v_mov_b64_e32 v[122:123], 0
	v_mov_b64_e32 v[124:125], 0
	v_mov_b64_e32 v[126:127], 0
	s_cmp_eq_u32 s100, 1
	s_cbranch_scc0 .Lgemm_nobar_1944
	s_mov_b32 s100, 0
	s_barrier

.LBB0_2020:
	s_add_u32 s55, s34, 0x100
	s_addc_u32 s56, s35, 0
	s_mov_b32 s57, -2
	v_mov_b64_e32 v[0:1], 0
	v_mov_b64_e32 v[2:3], 0
	v_mov_b64_e32 v[4:5], 0
	v_mov_b64_e32 v[6:7], 0
	v_mov_b64_e32 v[8:9], 0
	v_mov_b64_e32 v[10:11], 0
	v_mov_b64_e32 v[12:13], 0
	v_mov_b64_e32 v[14:15], 0
	v_mov_b64_e32 v[16:17], 0
	v_mov_b64_e32 v[18:19], 0
	v_mov_b64_e32 v[20:21], 0
	v_mov_b64_e32 v[22:23], 0
	v_mov_b64_e32 v[24:25], 0
	v_mov_b64_e32 v[26:27], 0
	v_mov_b64_e32 v[28:29], 0
	v_mov_b64_e32 v[30:31], 0
	v_mov_b64_e32 v[32:33], 0
	v_mov_b64_e32 v[34:35], 0
	v_mov_b64_e32 v[36:37], 0
	v_mov_b64_e32 v[38:39], 0
	v_mov_b64_e32 v[40:41], 0
	v_mov_b64_e32 v[42:43], 0
	v_mov_b64_e32 v[44:45], 0
	v_mov_b64_e32 v[46:47], 0
	v_mov_b64_e32 v[48:49], 0
	v_mov_b64_e32 v[50:51], 0
	v_mov_b64_e32 v[52:53], 0
	v_mov_b64_e32 v[54:55], 0
	v_mov_b64_e32 v[56:57], 0
	v_mov_b64_e32 v[58:59], 0
	v_mov_b64_e32 v[60:61], 0
	v_mov_b64_e32 v[62:63], 0
	v_mov_b64_e32 v[64:65], 0
	v_mov_b64_e32 v[66:67], 0
	v_mov_b64_e32 v[68:69], 0
	v_mov_b64_e32 v[70:71], 0
	v_mov_b64_e32 v[72:73], 0
	v_mov_b64_e32 v[74:75], 0
	v_mov_b64_e32 v[76:77], 0
	v_mov_b64_e32 v[78:79], 0
	v_mov_b64_e32 v[80:81], 0
	v_mov_b64_e32 v[82:83], 0
	v_mov_b64_e32 v[84:85], 0
	v_mov_b64_e32 v[86:87], 0
	v_mov_b64_e32 v[88:89], 0
	v_mov_b64_e32 v[90:91], 0
	v_mov_b64_e32 v[92:93], 0
	v_mov_b64_e32 v[94:95], 0
	v_mov_b64_e32 v[96:97], 0
	v_mov_b64_e32 v[98:99], 0
	v_mov_b64_e32 v[100:101], 0
	v_mov_b64_e32 v[102:103], 0
	v_mov_b64_e32 v[104:105], 0
	v_mov_b64_e32 v[106:107], 0
	v_mov_b64_e32 v[108:109], 0
	v_mov_b64_e32 v[110:111], 0
	v_mov_b64_e32 v[112:113], 0
	v_mov_b64_e32 v[114:115], 0
	v_mov_b64_e32 v[116:117], 0
	v_mov_b64_e32 v[118:119], 0
	v_mov_b64_e32 v[120:121], 0
	v_mov_b64_e32 v[122:123], 0
	v_mov_b64_e32 v[124:125], 0
	v_mov_b64_e32 v[126:127], 0
	s_cmp_eq_u32 s100, 1
	s_cbranch_scc0 .Lgemm_nobar_2012
	s_mov_b32 s100, 0
	s_barrier
